# FNet stage-1 items hand-pipelined (10-20 loads in flight) and all FNet items (2 stage-1 + ctx) on first-launched blocks; NA ctx items on blocks 0-255
# baseline (speedup 1.0000x reference)
.LBB0_667:
	v_readlane_b32 s0, v248, 0
	s_lshl_b32 s10, s0, 2
	v_lshrrev_b32_e32 v3, 6, v1
	v_add_u32_e32 v2, s10, v3
	s_lshl_b32 s13, s50, 2
	v_xad_u32 v2, v2, -1, s13
	s_movk_i32 s0, 0x3ff
	v_cmp_lt_i32_e32 vcc, s0, v2
	s_and_saveexec_b64 s[0:1], vcc
	s_cbranch_execz .LBB0_674
	v_lshrrev_b32_e32 v4, 2, v1
	v_and_b32_e32 v5, 8, v4
	v_mov_b32_e32 v67, 0
	v_lshlrev_b32_e32 v70, 1, v5
	v_mov_b32_e32 v71, v67
	v_lshl_add_u64 v[8:9], s[82:83], 0, v[70:71]
	s_mov_b64 s[6:7], 0xe90c000
	v_lshlrev_b32_e32 v66, 8, v132
	v_lshl_add_u64 v[72:73], v[8:9], 0, s[6:7]
	s_mov_b64 s[6:7], 0xc900000
	v_lshl_add_u64 v[74:75], v[8:9], 0, s[6:7]
	v_lshl_add_u64 v[8:9], s[82:83], 0, v[66:67]
	v_lshlrev_b32_e32 v66, 4, v131
	v_lshl_add_u64 v[8:9], v[8:9], 0, v[66:67]
	s_mov_b64 s[6:7], 0xe900000
	v_lshl_add_u64 v[76:77], v[8:9], 0, s[6:7]
	s_mov_b64 s[6:7], 0xe902000
	v_lshl_add_u64 v[78:79], v[8:9], 0, s[6:7]
	s_mov_b64 s[6:7], 0xe904000
	v_lshl_add_u64 v[80:81], v[8:9], 0, s[6:7]
	s_mov_b64 s[6:7], 0xe906000
	v_lshl_add_u64 v[82:83], v[8:9], 0, s[6:7]
	s_mov_b64 s[6:7], 0xe902020
	v_lshl_add_u64 v[84:85], v[8:9], 0, s[6:7]
	s_mov_b64 s[6:7], 0xe904020
	v_lshl_add_u64 v[86:87], v[8:9], 0, s[6:7]
	s_mov_b64 s[6:7], 0xe906020
	v_lshl_add_u64 v[88:89], v[8:9], 0, s[6:7]
	s_mov_b64 s[6:7], 0xe902040
	v_lshl_add_u64 v[90:91], v[8:9], 0, s[6:7]
	s_mov_b64 s[6:7], 0xe904040
	v_lshl_add_u64 v[92:93], v[8:9], 0, s[6:7]
	s_mov_b64 s[6:7], 0xe906040
	v_lshl_add_u64 v[94:95], v[8:9], 0, s[6:7]
	s_mov_b64 s[6:7], 0xe902060
	v_lshl_add_u64 v[96:97], v[8:9], 0, s[6:7]
	s_mov_b64 s[6:7], 0xe904060
	v_lshl_add_u64 v[98:99], v[8:9], 0, s[6:7]
	s_mov_b64 s[6:7], 0xe906060
	v_lshl_add_u64 v[100:101], v[8:9], 0, s[6:7]
	s_mov_b64 s[6:7], 0xe902080
	v_lshl_add_u64 v[102:103], v[8:9], 0, s[6:7]
	s_mov_b64 s[6:7], 0xe904080
	v_lshl_add_u64 v[104:105], v[8:9], 0, s[6:7]
	s_mov_b64 s[6:7], 0xe906080
	v_lshl_add_u64 v[106:107], v[8:9], 0, s[6:7]
	s_mov_b64 s[6:7], 0xe9020a0
	v_lshl_add_u64 v[108:109], v[8:9], 0, s[6:7]
	s_mov_b64 s[6:7], 0xe9040a0
	v_lshl_add_u64 v[110:111], v[8:9], 0, s[6:7]
	s_mov_b64 s[6:7], 0xe9060a0
	v_lshl_add_u64 v[112:113], v[8:9], 0, s[6:7]
	s_mov_b64 s[6:7], 0xe9020c0
	v_lshl_add_u64 v[114:115], v[8:9], 0, s[6:7]
	s_mov_b64 s[6:7], 0xe9040c0
	s_add_u32 s2, s82, 0x3000000
	v_lshl_add_u64 v[116:117], v[8:9], 0, s[6:7]
	s_mov_b64 s[6:7], 0xe9060c0
	s_addc_u32 s3, s83, 0
	v_lshl_add_u64 v[118:119], v[8:9], 0, s[6:7]
	s_mov_b64 s[6:7], 0xe9020e0
	s_add_u32 s4, s82, 0x3c00000
	v_lshl_add_u64 v[120:121], v[8:9], 0, s[6:7]
	s_mov_b64 s[6:7], 0xe9040e0
	s_addc_u32 s5, s83, 0
	v_lshl_add_u64 v[122:123], v[8:9], 0, s[6:7]
	s_mov_b64 s[6:7], 0xe9060e0
	v_lshl_add_u64 v[124:125], v[8:9], 0, s[6:7]
	s_add_u32 s6, s82, 0xe94c000
	v_or_b32_e32 v149, 32, v132
	s_addc_u32 s7, s83, 0
	v_sub_u32_e32 v3, s13, v3
	v_lshlrev_b32_e32 v4, 6, v132
	v_lshlrev_b32_e32 v6, 6, v149
	s_add_u32 s8, s82, 0xd500000
	v_subrev_u32_e32 v3, s10, v3
	v_or_b32_e32 v68, 0x200000, v134
	v_mov_b32_e32 v69, v67
	v_lshlrev_b32_e32 v148, 8, v131
	s_addc_u32 s9, s83, 0
	v_add_u32_e32 v71, 0xfffff7ff, v3
	v_lshlrev_b32_e32 v150, 4, v2
	s_lshl_b32 s16, s50, 6
	v_lshlrev_b32_e32 v151, 7, v2
	s_lshl_b32 s17, s50, 9
	s_mov_b64 s[10:11], 0
	s_movk_i32 s18, 0x7ff
	s_movk_i32 s19, 0x80
	s_mov_b32 s20, 0x8000
	s_mov_b32 s21, 0x10000
	s_mov_b32 s22, 0x18000
	s_mov_b32 s12, 0x3bb504f3
	s_movk_i32 s23, 0x1ff
	v_lshlrev_b32_e32 v126, 1, v134
	v_lshlrev_b32_e32 v128, 1, v4
	v_lshlrev_b32_e32 v136, 1, v6
	s_movk_i32 s24, 0x9ff
	s_branch .LBB0_670
.LBB0_669:
	s_or_b64 exec, exec, s[14:15]
	v_not_b32_e32 v2, v71
	v_add_u32_e32 v2, 0xfffffc00, v2
	v_add_u32_e32 v66, 0xfffffc00, v71
	v_cmp_gt_i32_e32 vcc, 0xfffffc00, v71
	v_cndmask_b32_e32 v2, v66, v2, vcc
	v_cmp_lt_i32_e32 vcc, -1, v71
	v_mov_b32_e32 v66, 0x7000
	v_cndmask_b32_e32 v71, v2, v66, vcc
	v_add_u32_e32 v2, 0x800, v71
	v_cmp_lt_i32_e32 vcc, s24, v2
	v_lshlrev_b32_e32 v150, 4, v2
	s_or_b64 s[10:11], vcc, s[10:11]
	v_lshlrev_b32_e32 v151, 7, v2
	s_andn2_b64 exec, exec, s[10:11]
	s_cbranch_execz .LBB0_674

.LBB0_1559:
	v_readlane_b32 s0, v248, 0
	s_lshl_b32 s10, s0, 2
	v_add_u32_e32 v2, s10, v186
	s_lshl_b32 s13, s50, 2
	v_xad_u32 v2, v2, -1, s13
	s_movk_i32 s0, 0x3ff
	v_cmp_lt_i32_e32 vcc, s0, v2
	s_and_saveexec_b64 s[0:1], vcc
	s_cbranch_execz .LBB0_1566
	v_and_b32_e32 v3, 8, v187
	v_mov_b32_e32 v67, 0
	v_lshlrev_b32_e32 v70, 1, v3
	v_mov_b32_e32 v71, v67
	v_lshl_add_u64 v[8:9], s[82:83], 0, v[70:71]
	s_mov_b64 s[6:7], 0xe90c000
	v_lshlrev_b32_e32 v66, 8, v132
	v_lshl_add_u64 v[72:73], v[8:9], 0, s[6:7]
	s_mov_b64 s[6:7], 0xc900000
	v_lshl_add_u64 v[74:75], v[8:9], 0, s[6:7]
	v_lshl_add_u64 v[8:9], s[82:83], 0, v[66:67]
	v_mov_b32_e32 v137, v67
	v_lshl_add_u64 v[8:9], v[8:9], 0, v[136:137]
	s_mov_b64 s[6:7], 0xe900000
	v_lshl_add_u64 v[76:77], v[8:9], 0, s[6:7]
	s_mov_b64 s[6:7], 0xe902000
	v_lshl_add_u64 v[78:79], v[8:9], 0, s[6:7]
	s_mov_b64 s[6:7], 0xe904000
	v_lshl_add_u64 v[80:81], v[8:9], 0, s[6:7]
	s_mov_b64 s[6:7], 0xe906000
	v_lshl_add_u64 v[82:83], v[8:9], 0, s[6:7]
	s_mov_b64 s[6:7], 0xe902020
	v_lshl_add_u64 v[84:85], v[8:9], 0, s[6:7]
	s_mov_b64 s[6:7], 0xe904020
	v_lshl_add_u64 v[86:87], v[8:9], 0, s[6:7]
	s_mov_b64 s[6:7], 0xe906020
	v_lshl_add_u64 v[88:89], v[8:9], 0, s[6:7]
	s_mov_b64 s[6:7], 0xe902040
	v_lshl_add_u64 v[90:91], v[8:9], 0, s[6:7]
	s_mov_b64 s[6:7], 0xe904040
	v_lshl_add_u64 v[92:93], v[8:9], 0, s[6:7]
	s_mov_b64 s[6:7], 0xe906040
	v_lshl_add_u64 v[94:95], v[8:9], 0, s[6:7]
	s_mov_b64 s[6:7], 0xe902060
	v_lshl_add_u64 v[96:97], v[8:9], 0, s[6:7]
	s_mov_b64 s[6:7], 0xe904060
	v_lshl_add_u64 v[98:99], v[8:9], 0, s[6:7]
	s_mov_b64 s[6:7], 0xe906060
	v_lshl_add_u64 v[100:101], v[8:9], 0, s[6:7]
	s_mov_b64 s[6:7], 0xe902080
	v_lshl_add_u64 v[102:103], v[8:9], 0, s[6:7]
	s_mov_b64 s[6:7], 0xe904080
	v_lshl_add_u64 v[104:105], v[8:9], 0, s[6:7]
	s_mov_b64 s[6:7], 0xe906080
	v_lshl_add_u64 v[106:107], v[8:9], 0, s[6:7]
	s_mov_b64 s[6:7], 0xe9020a0
	v_lshl_add_u64 v[108:109], v[8:9], 0, s[6:7]
	s_mov_b64 s[6:7], 0xe9040a0
	v_lshl_add_u64 v[110:111], v[8:9], 0, s[6:7]
	s_mov_b64 s[6:7], 0xe9060a0
	v_lshl_add_u64 v[112:113], v[8:9], 0, s[6:7]
	s_mov_b64 s[6:7], 0xe9020c0
	v_lshl_add_u64 v[114:115], v[8:9], 0, s[6:7]
	s_mov_b64 s[6:7], 0xe9040c0
	s_add_u32 s2, s82, 0x3000000
	v_lshl_add_u64 v[116:117], v[8:9], 0, s[6:7]
	s_mov_b64 s[6:7], 0xe9060c0
	s_addc_u32 s3, s83, 0
	v_lshl_add_u64 v[118:119], v[8:9], 0, s[6:7]
	s_mov_b64 s[6:7], 0xe9020e0
	s_add_u32 s4, s82, 0x3c00000
	v_lshl_add_u64 v[120:121], v[8:9], 0, s[6:7]
	s_mov_b64 s[6:7], 0xe9040e0
	s_addc_u32 s5, s83, 0
	v_lshl_add_u64 v[122:123], v[8:9], 0, s[6:7]
	s_mov_b64 s[6:7], 0xe9060e0
	v_lshl_add_u64 v[124:125], v[8:9], 0, s[6:7]
	s_add_u32 s6, s82, 0xe94c000
	v_or_b32_e32 v133, 32, v132
	s_addc_u32 s7, s83, 0
	v_sub_u32_e32 v3, s13, v186
	v_lshlrev_b32_e32 v4, 6, v132
	v_lshlrev_b32_e32 v6, 6, v133
	s_add_u32 s8, s82, 0xd500000
	v_subrev_u32_e32 v3, s10, v3
	v_or_b32_e32 v68, 0x200000, v134
	v_mov_b32_e32 v69, v67
	v_lshlrev_b32_e32 v131, 8, v131
	s_addc_u32 s9, s83, 0
	v_add_u32_e32 v71, 0xfffff7ff, v3
	v_lshlrev_b32_e32 v146, 4, v2
	s_lshl_b32 s16, s50, 6
	v_lshlrev_b32_e32 v147, 7, v2
	s_lshl_b32 s17, s50, 9
	s_mov_b64 s[10:11], 0
	s_movk_i32 s18, 0x7ff
	s_movk_i32 s19, 0x80
	s_mov_b32 s20, 0x8000
	s_mov_b32 s21, 0x10000
	s_mov_b32 s22, 0x18000
	s_mov_b32 s12, 0x3bb504f3
	s_movk_i32 s23, 0x1ff
	v_lshlrev_b32_e32 v126, 1, v134
	v_lshlrev_b32_e32 v128, 1, v4
	v_lshlrev_b32_e32 v134, 1, v6
	s_movk_i32 s24, 0x9ff
	s_branch .LBB0_1562
.LBB0_1561:
	s_or_b64 exec, exec, s[14:15]
	v_not_b32_e32 v2, v71
	v_add_u32_e32 v2, 0xfffffc00, v2
	v_add_u32_e32 v66, 0xfffffc00, v71
	v_cmp_gt_i32_e32 vcc, 0xfffffc00, v71
	v_cndmask_b32_e32 v2, v66, v2, vcc
	v_cmp_lt_i32_e32 vcc, -1, v71
	v_mov_b32_e32 v66, 0x7000
	v_cndmask_b32_e32 v71, v2, v66, vcc
	v_add_u32_e32 v2, 0x800, v71
	v_cmp_lt_i32_e32 vcc, s24, v2
	v_lshlrev_b32_e32 v146, 4, v2
	s_or_b64 s[10:11], vcc, s[10:11]
	v_lshlrev_b32_e32 v147, 7, v2
	s_andn2_b64 exec, exec, s[10:11]
	s_cbranch_execz .LBB0_1566
